# gating: the eight T-fragment LDS reads of a unit issued together after the barrier with counted lgkmcnt before each MFMA (was read, wait, MFMA eight times)
# speedup vs baseline: 1.0063x; 1.0063x over previous
; __device__ __forceinline__ unsigned pk2(float lo, float hi) { return pg8::cvt_pk_bf16(lo, hi); }
; __device__ __forceinline__ float bflo(unsigned w) { return __uint_as_float(w << 16); }
; __device__ __forceinline__ float bfhi(unsigned w) { return __uint_as_float(w & 0xffff0000u); }
; __device__ __forceinline__ void gate_phase(int bx, int G, bool skip_ctx, const bf16* __restrict__ VG, const bf16* __restrict__ U, const float* __restrict__ stats, ...
;     ...
;         f32x16 acc = {};
;         const bf16* trow = T + (db * 32 + r32) * GT_PITCH + hi * 8;
; #pragma unroll
;         for (int ks = 0; ks < 8; ++ks) {
;             const bf16x8 av = *(const bf16x8*)(trow + ks * 16);
;             acc = __builtin_amdgcn_mfma_f32_32x32x16_bf16(av, wcur[ks], acc, 0, 0, 0);
;         }
;         const size_t row = (size_t)chunk * 128 + p;
; #pragma unroll
;         for (int g4 = 0; g4 < 4; ++g4) {
;             const int d0 = db * 32 + 8 * g4 + 4 * hi;
;             u32x2 w;
;             w.x = pk2(bflo(ucur[g4].x) * (acc[4 * g4 + 0] + bias), bfhi(ucur[g4].x) * (acc[4 * g4 + 1] + bias));
;             w.y = pk2(bflo(ucur[g4].y) * (acc[4 * g4 + 2] + bias), bfhi(ucur[g4].y) * (acc[4 * g4 + 3] + bias));
;             *(u32x2*)(MIX + row * 1024 + 512 + h * 64 + d0) = w;
;         }
;         __syncthreads();
;         u = un;
.LBB0_44:
	s_waitcnt lgkmcnt(0)
	s_barrier
	ds_read_b128 v[4:7], v136
	ds_read_b128 v[138:141], v136 offset:32
	ds_read_b128 v[16:19], v136 offset:64
	ds_read_b128 v[20:23], v136 offset:96
	ds_read_b128 v[24:27], v136 offset:128
	ds_read_b128 v[188:191], v136 offset:160
	ds_read_b128 v[192:195], v136 offset:192
	ds_read_b128 v[196:199], v136 offset:224
	v_xor_b32_e32 v136, 0x8000, v136
	s_waitcnt lgkmcnt(7)
	v_mfma_f32_32x32x16_bf16 v[0:15], v[4:7], v[0:3], 0
	s_ashr_i32 s26, s13, 3
	s_ashr_i32 s27, s26, 31
	s_lshl_b64 s[26:27], s[26:27], 18
	s_lshl_b32 s72, s19, 1
	s_andn2_b64 vcc, exec, s[22:23]
	s_waitcnt lgkmcnt(6)
	v_mfma_f32_32x32x16_bf16 v[0:15], v[138:141], v[60:63], v[0:15]
	s_waitcnt lgkmcnt(5)
	v_mfma_f32_32x32x16_bf16 v[0:15], v[16:19], v[64:67], v[0:15]
	v_mov_b64_e32 v[64:65], v[76:77]
	v_mov_b64_e32 v[66:67], v[78:79]
	s_waitcnt lgkmcnt(4)
	v_mfma_f32_32x32x16_bf16 v[0:15], v[20:23], v[52:55], v[0:15]
	v_mov_b64_e32 v[60:61], v[72:73]
	v_mov_b64_e32 v[62:63], v[74:75]
	s_waitcnt lgkmcnt(3)
	v_mfma_f32_32x32x16_bf16 v[0:15], v[24:27], v[56:59], v[0:15]
	v_mov_b64_e32 v[56:57], v[84:85]
	v_mov_b64_e32 v[58:59], v[86:87]
	s_waitcnt lgkmcnt(2)
	v_mfma_f32_32x32x16_bf16 v[0:15], v[188:191], v[48:51], v[0:15]
	v_mov_b64_e32 v[52:53], v[80:81]
	v_mov_b64_e32 v[54:55], v[82:83]
	s_waitcnt lgkmcnt(1)
	v_mfma_f32_32x32x16_bf16 v[0:15], v[192:195], v[44:47], v[0:15]
	v_mov_b64_e32 v[48:49], v[88:89]
	v_mov_b64_e32 v[50:51], v[90:91]
	s_waitcnt lgkmcnt(0)
	v_mfma_f32_32x32x16_bf16 v[0:15], v[196:199], v[40:43], v[0:15]
	v_lshlrev_b32_e32 v42, 16, v124
	v_lshl_add_u64 v[40:41], v[112:113], 0, s[26:27]
	v_lshl_add_u64 v[40:41], v[40:41], 0, s[72:73]
	v_mov_b64_e32 v[44:45], v[92:93]
	v_mov_b64_e32 v[46:47], v[94:95]
	s_nop 10
	v_add_f32_e32 v0, v137, v0
	v_mul_f32_e32 v0, v0, v42
	v_and_b32_e32 v42, 0xffff0000, v124
	v_add_f32_e32 v1, v137, v1
	v_mul_f32_e32 v1, v1, v42
	v_cvt_pk_bf16_f32 v172, v0, v1
	v_lshlrev_b32_e32 v0, 16, v125
	v_add_f32_e32 v1, v137, v2
	v_mul_f32_e32 v0, v1, v0
	v_and_b32_e32 v1, 0xffff0000, v125
	v_add_f32_e32 v2, v137, v3
	v_mul_f32_e32 v1, v2, v1
	v_lshlrev_b32_e32 v2, 16, v122
	v_add_f32_e32 v3, v137, v4
	v_mul_f32_e32 v2, v3, v2
	v_and_b32_e32 v3, 0xffff0000, v122
	v_add_f32_e32 v4, v137, v5
	v_cvt_pk_bf16_f32 v173, v0, v1
	v_lshl_add_u64 v[0:1], v[40:41], 0, v[160:161]
	v_mul_f32_e32 v3, v4, v3
	v_cvt_pk_bf16_f32 v176, v2, v3
	v_lshlrev_b32_e32 v3, 16, v123
	v_add_f32_e32 v4, v137, v6
	v_mul_f32_e32 v3, v4, v3
	v_and_b32_e32 v4, 0xffff0000, v123
	v_add_f32_e32 v5, v137, v7
	v_mul_f32_e32 v4, v5, v4
	v_cvt_pk_bf16_f32 v177, v3, v4
	v_lshlrev_b32_e32 v2, 16, v120
	v_add_f32_e32 v3, v137, v8
	v_mul_f32_e32 v2, v3, v2
	v_and_b32_e32 v3, 0xffff0000, v120
	v_add_f32_e32 v4, v137, v9
	v_mul_f32_e32 v3, v4, v3
	v_cvt_pk_bf16_f32 v174, v2, v3
	v_lshlrev_b32_e32 v3, 16, v121
	v_add_f32_e32 v4, v137, v10
	v_mul_f32_e32 v3, v4, v3
	v_and_b32_e32 v4, 0xffff0000, v121
	v_add_f32_e32 v5, v137, v11
	v_mul_f32_e32 v4, v5, v4
	v_cvt_pk_bf16_f32 v175, v3, v4
	v_lshlrev_b32_e32 v2, 16, v106
	v_add_f32_e32 v3, v137, v12
	v_mul_f32_e32 v2, v3, v2
	v_and_b32_e32 v3, 0xffff0000, v106
	v_add_f32_e32 v4, v137, v13
	v_mul_f32_e32 v3, v4, v3
	v_cvt_pk_bf16_f32 v178, v2, v3
	v_lshlrev_b32_e32 v3, 16, v107
	v_add_f32_e32 v4, v137, v14
	v_mul_f32_e32 v3, v4, v3
	v_and_b32_e32 v4, 0xffff0000, v107
	v_add_f32_e32 v5, v137, v15
	v_mul_f32_e32 v4, v5, v4
	v_cvt_pk_bf16_f32 v179, v3, v4
	s_nop 1
	v_permlane32_swap_b32_e32 v172, v174
	v_permlane32_swap_b32_e32 v173, v175
	v_permlane32_swap_b32_e32 v176, v178
	v_permlane32_swap_b32_e32 v177, v179
	global_store_dwordx4 v[0:1], v[172:175], off offset:1024
	global_store_dwordx4 v[0:1], v[176:179], off offset:1040
	s_waitcnt vmcnt(2)
	v_permlane32_swap_b32_e32 v126, v128
	v_permlane32_swap_b32_e32 v127, v129
	v_permlane32_swap_b32_e32 v130, v132
	v_permlane32_swap_b32_e32 v131, v133
	v_mov_b64_e32 v[0:1], v[68:69]
	v_mov_b64_e32 v[40:41], v[96:97]
	v_mov_b64_e32 v[124:125], v[126:127]
	v_mov_b64_e32 v[122:123], v[130:131]
	v_mov_b64_e32 v[120:121], v[128:129]
	v_mov_b64_e32 v[106:107], v[132:133]
	v_mov_b64_e32 v[2:3], v[70:71]
	v_mov_b64_e32 v[42:43], v[98:99]
	v_xor_b32_e32 v134, 0x8000, v134
	v_xor_b32_e32 v135, 0x8000, v135
	s_cbranch_vccnz .LBB0_51
